# top-13 block ranking: candidate loop unrolled by 4 with immediate lane selects
# speedup vs baseline: 1.0159x; 1.0137x over previous
; __device__ __forceinline__ void nsa_prompt_unit(Frame& F, int l, int b, int kvh, int c) {
;     ...
;         const int n = lane; const bool cand = (n >= 1) && (n <= c - 2);
;         const unsigned long long forced = 1ull | (1ull << c) | (c >= 1 ? (1ull << (c - 1)) : 0ull);
;         unsigned long long um = 0ull;
; #pragma unroll 1
;         for (int qq = 0; qq < 8; ++qq) { const int q = w * 8 + qq;
;             const unsigned kb_ = cand ? ((__float_as_uint(imp[q * 65 + n]) & ~63u) | (unsigned)(63 - n)) : 0u;
;             int rank = 0;
;             for (int j = 1; j <= c - 2; ++j) { const unsigned sj = __builtin_amdgcn_readlane(kb_, j); rank += (sj > kb_) ? 1 : 0; }
;             const unsigned long long m = __ballot(cand && rank < 13) | forced;
.LBB0_833:
	s_or_b64 exec, exec, s[30:31]
	s_andn2_b64 vcc, exec, s[26:27]
	s_mov_b64 s[30:31], -1
	s_cbranch_vccnz .LBB0_837
	v_mov_b32_e32 v24, 0
	v_readlane_b32 s68, v23, 1
	v_readlane_b32 s69, v23, 2
	v_readlane_b32 s70, v23, 3
	v_readlane_b32 s71, v23, 4
	v_cmp_gt_u32_e64 s[46:47], s68, v23
	v_cmp_gt_u32_e64 s[48:49], s69, v23
	v_cmp_gt_u32_e64 s[72:73], s70, v23
	v_cmp_gt_u32_e64 s[76:77], s71, v23
	v_addc_co_u32_e64 v24, vcc, 0, v24, s[46:47]
	v_addc_co_u32_e64 v24, vcc, 0, v24, s[48:49]
	v_addc_co_u32_e64 v24, vcc, 0, v24, s[72:73]
	v_addc_co_u32_e64 v24, vcc, 0, v24, s[76:77]
	s_cmp_lt_u32 s8, 7
	s_cbranch_scc1 .Ltk_done
	v_readlane_b32 s68, v23, 5
	v_readlane_b32 s69, v23, 6
	v_readlane_b32 s70, v23, 7
	v_readlane_b32 s71, v23, 8
	v_cmp_gt_u32_e64 s[46:47], s68, v23
	v_cmp_gt_u32_e64 s[48:49], s69, v23
	v_cmp_gt_u32_e64 s[72:73], s70, v23
	v_cmp_gt_u32_e64 s[76:77], s71, v23
	v_addc_co_u32_e64 v24, vcc, 0, v24, s[46:47]
	v_addc_co_u32_e64 v24, vcc, 0, v24, s[48:49]
	v_addc_co_u32_e64 v24, vcc, 0, v24, s[72:73]
	v_addc_co_u32_e64 v24, vcc, 0, v24, s[76:77]
	s_cmp_lt_u32 s8, 11
	s_cbranch_scc1 .Ltk_done
	v_readlane_b32 s68, v23, 9
	v_readlane_b32 s69, v23, 10
	v_readlane_b32 s70, v23, 11
	v_readlane_b32 s71, v23, 12
	v_cmp_gt_u32_e64 s[46:47], s68, v23
	v_cmp_gt_u32_e64 s[48:49], s69, v23
	v_cmp_gt_u32_e64 s[72:73], s70, v23
	v_cmp_gt_u32_e64 s[76:77], s71, v23
	v_addc_co_u32_e64 v24, vcc, 0, v24, s[46:47]
	v_addc_co_u32_e64 v24, vcc, 0, v24, s[48:49]
	v_addc_co_u32_e64 v24, vcc, 0, v24, s[72:73]
	v_addc_co_u32_e64 v24, vcc, 0, v24, s[76:77]
	s_cmp_lt_u32 s8, 15
	s_cbranch_scc1 .Ltk_done
	v_readlane_b32 s68, v23, 13
	v_readlane_b32 s69, v23, 14
	v_readlane_b32 s70, v23, 15
	v_readlane_b32 s71, v23, 16
	v_cmp_gt_u32_e64 s[46:47], s68, v23
	v_cmp_gt_u32_e64 s[48:49], s69, v23
	v_cmp_gt_u32_e64 s[72:73], s70, v23
	v_cmp_gt_u32_e64 s[76:77], s71, v23
	v_addc_co_u32_e64 v24, vcc, 0, v24, s[46:47]
	v_addc_co_u32_e64 v24, vcc, 0, v24, s[48:49]
	v_addc_co_u32_e64 v24, vcc, 0, v24, s[72:73]
	v_addc_co_u32_e64 v24, vcc, 0, v24, s[76:77]
	s_cmp_lt_u32 s8, 19
	s_cbranch_scc1 .Ltk_done
	v_readlane_b32 s68, v23, 17
	v_readlane_b32 s69, v23, 18
	v_readlane_b32 s70, v23, 19
	v_readlane_b32 s71, v23, 20
	v_cmp_gt_u32_e64 s[46:47], s68, v23
	v_cmp_gt_u32_e64 s[48:49], s69, v23
	v_cmp_gt_u32_e64 s[72:73], s70, v23
	v_cmp_gt_u32_e64 s[76:77], s71, v23
	v_addc_co_u32_e64 v24, vcc, 0, v24, s[46:47]
	v_addc_co_u32_e64 v24, vcc, 0, v24, s[48:49]
	v_addc_co_u32_e64 v24, vcc, 0, v24, s[72:73]
	v_addc_co_u32_e64 v24, vcc, 0, v24, s[76:77]
	s_cmp_lt_u32 s8, 23
	s_cbranch_scc1 .Ltk_done
	v_readlane_b32 s68, v23, 21
	v_readlane_b32 s69, v23, 22
	v_readlane_b32 s70, v23, 23
	v_readlane_b32 s71, v23, 24
	v_cmp_gt_u32_e64 s[46:47], s68, v23
	v_cmp_gt_u32_e64 s[48:49], s69, v23
	v_cmp_gt_u32_e64 s[72:73], s70, v23
	v_cmp_gt_u32_e64 s[76:77], s71, v23
	v_addc_co_u32_e64 v24, vcc, 0, v24, s[46:47]
	v_addc_co_u32_e64 v24, vcc, 0, v24, s[48:49]
	v_addc_co_u32_e64 v24, vcc, 0, v24, s[72:73]
	v_addc_co_u32_e64 v24, vcc, 0, v24, s[76:77]
	s_cmp_lt_u32 s8, 27
	s_cbranch_scc1 .Ltk_done
	v_readlane_b32 s68, v23, 25
	v_readlane_b32 s69, v23, 26
	v_readlane_b32 s70, v23, 27
	v_readlane_b32 s71, v23, 28
	v_cmp_gt_u32_e64 s[46:47], s68, v23
	v_cmp_gt_u32_e64 s[48:49], s69, v23
	v_cmp_gt_u32_e64 s[72:73], s70, v23
	v_cmp_gt_u32_e64 s[76:77], s71, v23
	v_addc_co_u32_e64 v24, vcc, 0, v24, s[46:47]
	v_addc_co_u32_e64 v24, vcc, 0, v24, s[48:49]
	v_addc_co_u32_e64 v24, vcc, 0, v24, s[72:73]
	v_addc_co_u32_e64 v24, vcc, 0, v24, s[76:77]
	s_cmp_lt_u32 s8, 31
	s_cbranch_scc1 .Ltk_done
	v_readlane_b32 s68, v23, 29
	v_readlane_b32 s69, v23, 30
	v_readlane_b32 s70, v23, 31
	v_readlane_b32 s71, v23, 32
	v_cmp_gt_u32_e64 s[46:47], s68, v23
	v_cmp_gt_u32_e64 s[48:49], s69, v23
	v_cmp_gt_u32_e64 s[72:73], s70, v23
	v_cmp_gt_u32_e64 s[76:77], s71, v23
	v_addc_co_u32_e64 v24, vcc, 0, v24, s[46:47]
	v_addc_co_u32_e64 v24, vcc, 0, v24, s[48:49]
	v_addc_co_u32_e64 v24, vcc, 0, v24, s[72:73]
	v_addc_co_u32_e64 v24, vcc, 0, v24, s[76:77]
	s_cmp_lt_u32 s8, 35
	s_cbranch_scc1 .Ltk_done
; __device__ __forceinline__ void nsa_prompt_unit(Frame& F, int l, int b, int kvh, int c) {
;     ...
;         for (int qq = 0; qq < 8; ++qq) { const int q = w * 8 + qq;
;             const unsigned kb_ = cand ? ((__float_as_uint(imp[q * 65 + n]) & ~63u) | (unsigned)(63 - n)) : 0u;
;             int rank = 0;
;             for (int j = 1; j <= c - 2; ++j) { const unsigned sj = __builtin_amdgcn_readlane(kb_, j); rank += (sj > kb_) ? 1 : 0; }
;             const unsigned long long m = __ballot(cand && rank < 13) | forced;
	v_readlane_b32 s68, v23, 33
	v_readlane_b32 s69, v23, 34
	v_readlane_b32 s70, v23, 35
	v_readlane_b32 s71, v23, 36
	v_cmp_gt_u32_e64 s[46:47], s68, v23
	v_cmp_gt_u32_e64 s[48:49], s69, v23
	v_cmp_gt_u32_e64 s[72:73], s70, v23
	v_cmp_gt_u32_e64 s[76:77], s71, v23
	v_addc_co_u32_e64 v24, vcc, 0, v24, s[46:47]
	v_addc_co_u32_e64 v24, vcc, 0, v24, s[48:49]
	v_addc_co_u32_e64 v24, vcc, 0, v24, s[72:73]
	v_addc_co_u32_e64 v24, vcc, 0, v24, s[76:77]
	s_cmp_lt_u32 s8, 39
	s_cbranch_scc1 .Ltk_done
	v_readlane_b32 s68, v23, 37
	v_readlane_b32 s69, v23, 38
	v_readlane_b32 s70, v23, 39
	v_readlane_b32 s71, v23, 40
	v_cmp_gt_u32_e64 s[46:47], s68, v23
	v_cmp_gt_u32_e64 s[48:49], s69, v23
	v_cmp_gt_u32_e64 s[72:73], s70, v23
	v_cmp_gt_u32_e64 s[76:77], s71, v23
	v_addc_co_u32_e64 v24, vcc, 0, v24, s[46:47]
	v_addc_co_u32_e64 v24, vcc, 0, v24, s[48:49]
	v_addc_co_u32_e64 v24, vcc, 0, v24, s[72:73]
	v_addc_co_u32_e64 v24, vcc, 0, v24, s[76:77]
	s_cmp_lt_u32 s8, 43
	s_cbranch_scc1 .Ltk_done
	v_readlane_b32 s68, v23, 41
	v_readlane_b32 s69, v23, 42
	v_readlane_b32 s70, v23, 43
	v_readlane_b32 s71, v23, 44
	v_cmp_gt_u32_e64 s[46:47], s68, v23
	v_cmp_gt_u32_e64 s[48:49], s69, v23
	v_cmp_gt_u32_e64 s[72:73], s70, v23
	v_cmp_gt_u32_e64 s[76:77], s71, v23
	v_addc_co_u32_e64 v24, vcc, 0, v24, s[46:47]
	v_addc_co_u32_e64 v24, vcc, 0, v24, s[48:49]
	v_addc_co_u32_e64 v24, vcc, 0, v24, s[72:73]
	v_addc_co_u32_e64 v24, vcc, 0, v24, s[76:77]
	s_cmp_lt_u32 s8, 47
	s_cbranch_scc1 .Ltk_done
	v_readlane_b32 s68, v23, 45
	v_readlane_b32 s69, v23, 46
	v_readlane_b32 s70, v23, 47
	v_readlane_b32 s71, v23, 48
	v_cmp_gt_u32_e64 s[46:47], s68, v23
	v_cmp_gt_u32_e64 s[48:49], s69, v23
	v_cmp_gt_u32_e64 s[72:73], s70, v23
	v_cmp_gt_u32_e64 s[76:77], s71, v23
	v_addc_co_u32_e64 v24, vcc, 0, v24, s[46:47]
	v_addc_co_u32_e64 v24, vcc, 0, v24, s[48:49]
	v_addc_co_u32_e64 v24, vcc, 0, v24, s[72:73]
	v_addc_co_u32_e64 v24, vcc, 0, v24, s[76:77]
	s_cmp_lt_u32 s8, 51
	s_cbranch_scc1 .Ltk_done
	v_readlane_b32 s68, v23, 49
	v_readlane_b32 s69, v23, 50
	v_readlane_b32 s70, v23, 51
	v_readlane_b32 s71, v23, 52
	v_cmp_gt_u32_e64 s[46:47], s68, v23
	v_cmp_gt_u32_e64 s[48:49], s69, v23
	v_cmp_gt_u32_e64 s[72:73], s70, v23
	v_cmp_gt_u32_e64 s[76:77], s71, v23
	v_addc_co_u32_e64 v24, vcc, 0, v24, s[46:47]
	v_addc_co_u32_e64 v24, vcc, 0, v24, s[48:49]
	v_addc_co_u32_e64 v24, vcc, 0, v24, s[72:73]
	v_addc_co_u32_e64 v24, vcc, 0, v24, s[76:77]
	s_cmp_lt_u32 s8, 55
	s_cbranch_scc1 .Ltk_done
	v_readlane_b32 s68, v23, 53
	v_readlane_b32 s69, v23, 54
	v_readlane_b32 s70, v23, 55
	v_readlane_b32 s71, v23, 56
	v_cmp_gt_u32_e64 s[46:47], s68, v23
	v_cmp_gt_u32_e64 s[48:49], s69, v23
	v_cmp_gt_u32_e64 s[72:73], s70, v23
	v_cmp_gt_u32_e64 s[76:77], s71, v23
	v_addc_co_u32_e64 v24, vcc, 0, v24, s[46:47]
	v_addc_co_u32_e64 v24, vcc, 0, v24, s[48:49]
	v_addc_co_u32_e64 v24, vcc, 0, v24, s[72:73]
	v_addc_co_u32_e64 v24, vcc, 0, v24, s[76:77]
	s_cmp_lt_u32 s8, 59
	s_cbranch_scc1 .Ltk_done
	v_readlane_b32 s68, v23, 57
	v_readlane_b32 s69, v23, 58
	v_readlane_b32 s70, v23, 59
	v_readlane_b32 s71, v23, 60
	v_cmp_gt_u32_e64 s[46:47], s68, v23
	v_cmp_gt_u32_e64 s[48:49], s69, v23
	v_cmp_gt_u32_e64 s[72:73], s70, v23
	v_cmp_gt_u32_e64 s[76:77], s71, v23
	v_addc_co_u32_e64 v24, vcc, 0, v24, s[46:47]
	v_addc_co_u32_e64 v24, vcc, 0, v24, s[48:49]
	v_addc_co_u32_e64 v24, vcc, 0, v24, s[72:73]
	v_addc_co_u32_e64 v24, vcc, 0, v24, s[76:77]
	s_cmp_lt_u32 s8, 63
	s_cbranch_scc1 .Ltk_done
	v_readlane_b32 s68, v23, 61
	v_readlane_b32 s69, v23, 62
	v_readlane_b32 s70, v23, 63
	v_cmp_gt_u32_e64 s[46:47], s68, v23
	v_cmp_gt_u32_e64 s[48:49], s69, v23
	v_cmp_gt_u32_e64 s[72:73], s70, v23
	v_addc_co_u32_e64 v24, vcc, 0, v24, s[46:47]
	v_addc_co_u32_e64 v24, vcc, 0, v24, s[48:49]
	v_addc_co_u32_e64 v24, vcc, 0, v24, s[72:73]
.Ltk_done:
	v_cmp_gt_u32_e64 s[30:31], 13, v24
